# attention row-max cross-half exchange via v_permlane32_swap instead of ds_bpermute
# speedup vs baseline: 1.0664x; 1.0009x over previous
; DI float fexp2(float x) { return __builtin_amdgcn_exp2f(x); }
; DI float shx(float v, int mask, int lane) { return __int_as_float(__builtin_amdgcn_ds_bpermute(((lane ^ mask) & 63) << 2, __float_as_int(v))); }
; DI void attn_item(const Params& p, int l, int b, int head, int qt, float lam, float lam_init, unsigned char* smem) {
;     ...
; #pragma unroll
;       for (int sub = 0; sub < 2; ++sub)
; #pragma unroll
;         for (int i = 0; i < 16; ++i) mx = fmaxf(mx, s[sub][i]);
;       mx = fmaxf(mx, shx(mx, 32, lane));
;       const bool livelane = !(mx - m_run < -150.f);
;       if (__ballot(livelane) != 0ull) {
;         const float m_new = fmaxf(m_run, mx);
;         const float alpha = fexp2(m_run - m_new);
;         m_run = m_new;
;         float lsum = 0.f;
; #pragma unroll
;         for (int sub = 0; sub < 2; ++sub)
; #pragma unroll
;           for (int i = 0; i < 16; ++i) {
;             const float pv = fexp2(s[sub][i] - m_new);
;             lsum += pv;
;             s[sub][i] = pv;
;           }
;         l_run = l_run * alpha + lsum;
;         if (__ballot(alpha != 1.f) != 0ull) {
; #pragma unroll
;           for (int dt = 0; dt < 4; ++dt)
; #pragma unroll
;             for (int i = 0; i < 16; ++i) O[dt][i] *= alpha;
;         }
.LBB0_480:
	s_or_b64 exec, exec, s[0:1]
	s_mov_b32 s0, 0xff800000
	s_nop 4
	v_max3_f32 v190, v80, s0, v81
	v_max3_f32 v190, v190, v82, v83
	v_max3_f32 v190, v190, v84, v85
	v_max3_f32 v190, v190, v86, v87
	v_max3_f32 v190, v190, v88, v89
	v_max3_f32 v190, v190, v90, v91
	v_max3_f32 v190, v190, v92, v93
	v_max3_f32 v190, v190, v94, v95
	v_max3_f32 v190, v190, v64, v65
	v_max3_f32 v190, v190, v66, v67
	v_max3_f32 v190, v190, v68, v69
	v_max3_f32 v190, v190, v70, v71
	v_max3_f32 v190, v190, v72, v73
	v_max3_f32 v190, v190, v74, v75
	v_max3_f32 v190, v190, v76, v77
	v_max3_f32 v190, v190, v78, v79
	v_mov_b32_e32 v192, v190
	s_mov_b32 s0, 0xc3160000
	s_nop 1
	v_permlane32_swap_b32_e32 v190, v192
	v_max_f32_e32 v192, v192, v192
	v_max_f32_e32 v190, v190, v192
	v_sub_f32_e32 v192, v190, v174
	v_cmp_ngt_f32_e32 vcc, s0, v192
	s_cbranch_vccz .LBB0_484
	v_max_f32_e32 v190, v190, v190
	v_max_f32_e32 v192, v174, v174
	v_max_f32_e32 v190, v192, v190
	v_sub_f32_e32 v174, v174, v190
	v_exp_f32_e32 v174, v174
	s_nop 0
	v_cmp_neq_f32_e32 vcc, 1.0, v174
	s_cbranch_vccz .LBB0_483
	v_pk_mul_f32 v[62:63], v[62:63], v[174:175] op_sel_hi:[1,0]
	v_pk_mul_f32 v[60:61], v[60:61], v[174:175] op_sel_hi:[1,0]
	v_pk_mul_f32 v[58:59], v[58:59], v[174:175] op_sel_hi:[1,0]
	v_pk_mul_f32 v[56:57], v[56:57], v[174:175] op_sel_hi:[1,0]
	v_pk_mul_f32 v[54:55], v[54:55], v[174:175] op_sel_hi:[1,0]
	v_pk_mul_f32 v[52:53], v[52:53], v[174:175] op_sel_hi:[1,0]
	v_pk_mul_f32 v[50:51], v[50:51], v[174:175] op_sel_hi:[1,0]
	v_pk_mul_f32 v[48:49], v[48:49], v[174:175] op_sel_hi:[1,0]
	v_pk_mul_f32 v[46:47], v[46:47], v[174:175] op_sel_hi:[1,0]
	v_pk_mul_f32 v[44:45], v[44:45], v[174:175] op_sel_hi:[1,0]
	v_pk_mul_f32 v[42:43], v[42:43], v[174:175] op_sel_hi:[1,0]
	v_pk_mul_f32 v[40:41], v[40:41], v[174:175] op_sel_hi:[1,0]
	v_pk_mul_f32 v[38:39], v[38:39], v[174:175] op_sel_hi:[1,0]
	v_pk_mul_f32 v[36:37], v[36:37], v[174:175] op_sel_hi:[1,0]
	v_pk_mul_f32 v[34:35], v[34:35], v[174:175] op_sel_hi:[1,0]
	v_pk_mul_f32 v[32:33], v[32:33], v[174:175] op_sel_hi:[1,0]
	v_pk_mul_f32 v[30:31], v[30:31], v[174:175] op_sel_hi:[1,0]
	v_pk_mul_f32 v[28:29], v[28:29], v[174:175] op_sel_hi:[1,0]
	v_pk_mul_f32 v[26:27], v[26:27], v[174:175] op_sel_hi:[1,0]
	v_pk_mul_f32 v[24:25], v[24:25], v[174:175] op_sel_hi:[1,0]
	v_pk_mul_f32 v[22:23], v[22:23], v[174:175] op_sel_hi:[1,0]
	v_pk_mul_f32 v[20:21], v[20:21], v[174:175] op_sel_hi:[1,0]
	v_pk_mul_f32 v[18:19], v[18:19], v[174:175] op_sel_hi:[1,0]
	v_pk_mul_f32 v[16:17], v[16:17], v[174:175] op_sel_hi:[1,0]
	v_pk_mul_f32 v[14:15], v[14:15], v[174:175] op_sel_hi:[1,0]
	v_pk_mul_f32 v[12:13], v[12:13], v[174:175] op_sel_hi:[1,0]
	v_pk_mul_f32 v[10:11], v[10:11], v[174:175] op_sel_hi:[1,0]
	v_pk_mul_f32 v[8:9], v[8:9], v[174:175] op_sel_hi:[1,0]
	v_pk_mul_f32 v[6:7], v[6:7], v[174:175] op_sel_hi:[1,0]
	v_pk_mul_f32 v[4:5], v[4:5], v[174:175] op_sel_hi:[1,0]
	v_pk_mul_f32 v[2:3], v[2:3], v[174:175] op_sel_hi:[1,0]
	v_pk_mul_f32 v[0:1], v[0:1], v[174:175] op_sel_hi:[1,0]
